# hyena: filter->LDS copy issues its 8 loads together for prompt units; phase-0 layer-2/3 sin stages prefetch the 31 bias values (20 in flight)
# baseline (speedup 1.0000x reference)
; __device__ __forceinline__ int crow16(int r, int hi) { return (r & 3) + 8 * (r >> 2) + 4 * hi; }
; __device__ __forceinline__ void filter_item32(const Args& a, int L, bf16* KR, int t0, int np0, int npn, int lane) {
;     ...
;         for (int r = 0; r < 16; ++r) { const int j = crow16(r, hi); h0[r] = sinf(fq[j] * (g0[r] + bb[j])); h1[r] = sinf(fq[32 + j] * (g1[r] + bb[32 + j])); }
.LBB0_187:
	s_andn2_saveexec_b64 s[2:3], s[12:13]
	v_mul_f32_e64 v18, |v1|, s1
	v_rndne_f32_e32 v18, v18
	v_cvt_i32_f32_e32 v37, v18
	v_fma_f32 v38, v18, s92, |v1|
	v_fmac_f32_e32 v38, 0xb3a22168, v18
	v_fmac_f32_e32 v38, 0xa7c234c4, v18
	s_or_b64 exec, exec, s[2:3]
	v_lshl_add_u64 v[34:35], s[10:11], 0, v[80:81]
	global_load_dword v234, v[34:35], off offset:128
	global_load_dword v235, v[34:35], off offset:4
	global_load_dword v236, v[34:35], off offset:132
	global_load_dword v237, v[34:35], off offset:8
	global_load_dword v238, v[34:35], off offset:136
	global_load_dword v239, v[34:35], off offset:12
	global_load_dword v240, v[34:35], off offset:140
	global_load_dword v241, v[34:35], off offset:32
	global_load_dword v244, v[34:35], off offset:160
	global_load_dword v245, v[34:35], off offset:36
	global_load_dword v246, v[34:35], off offset:164
	global_load_dword v247, v[34:35], off offset:40
	global_load_dword v248, v[34:35], off offset:168
	global_load_dword v249, v[34:35], off offset:44
	global_load_dword v250, v[34:35], off offset:172
	global_load_dword v251, v[34:35], off offset:64
	global_load_dword v252, v[34:35], off offset:192
	global_load_dword v253, v[34:35], off offset:68
	global_load_dword v254, v[34:35], off offset:196
	global_load_dword v255, v[34:35], off offset:72
	s_waitcnt vmcnt(19)
	v_mov_b32_e32 v18, v234
	global_load_dword v234, v[34:35], off offset:200
	s_nop 0
	v_add_f32_e32 v2, v2, v18
	v_mul_f32_e32 v18, v66, v2
	v_and_b32_e32 v48, 0x7fffffff, v18
	v_cmp_nlt_f32_e64 s[2:3], |v18|, s60
	s_and_saveexec_b64 s[4:5], s[2:3]
	s_xor_b64 s[10:11], exec, s[4:5]
	s_cbranch_execnz .Lsl_191
.LBB0_191:
	s_andn2_saveexec_b64 s[2:3], s[10:11]
	v_mul_f32_e64 v2, |v18|, s1
	v_rndne_f32_e32 v2, v2
	v_cvt_i32_f32_e32 v49, v2
	v_fma_f32 v50, v2, s92, |v18|
	v_fmac_f32_e32 v50, 0xb3a22168, v2
	v_fmac_f32_e32 v50, 0xa7c234c4, v2
	s_or_b64 exec, exec, s[2:3]
	s_waitcnt vmcnt(19)
	v_mov_b32_e32 v2, v235
	global_load_dword v235, v[34:35], off offset:76
	v_add_f32_e32 v2, v19, v2
	v_mul_f32_e32 v39, v67, v2
	v_and_b32_e32 v40, 0x7fffffff, v39
	v_cmp_nlt_f32_e64 s[2:3], |v39|, s60
	s_and_saveexec_b64 s[4:5], s[2:3]
	s_xor_b64 s[10:11], exec, s[4:5]
	s_cbranch_execnz .Lsl_195
.LBB0_195:
	s_andn2_saveexec_b64 s[2:3], s[10:11]
	v_mul_f32_e64 v2, |v39|, s1
	v_rndne_f32_e32 v2, v2
	v_cvt_i32_f32_e32 v41, v2
	v_fma_f32 v42, v2, s92, |v39|
	v_fmac_f32_e32 v42, 0xb3a22168, v2
	v_fmac_f32_e32 v42, 0xa7c234c4, v2
	s_or_b64 exec, exec, s[2:3]
	s_waitcnt vmcnt(19)
	v_mov_b32_e32 v2, v236
	global_load_dword v236, v[34:35], off offset:204
	v_add_f32_e32 v2, v3, v2
	v_mul_f32_e32 v3, v68, v2
	v_and_b32_e32 v19, 0x7fffffff, v3
	v_cmp_nlt_f32_e64 s[2:3], |v3|, s60
	s_and_saveexec_b64 s[4:5], s[2:3]
	s_xor_b64 s[10:11], exec, s[4:5]
	s_cbranch_execnz .Lsl_199
.LBB0_199:
	s_andn2_saveexec_b64 s[2:3], s[10:11]
	v_mul_f32_e64 v2, |v3|, s1
	v_rndne_f32_e32 v2, v2
	v_cvt_i32_f32_e32 v51, v2
	v_fma_f32 v52, v2, s92, |v3|
	v_fmac_f32_e32 v52, 0xb3a22168, v2
	v_fmac_f32_e32 v52, 0xa7c234c4, v2
	s_or_b64 exec, exec, s[2:3]
	s_waitcnt vmcnt(19)
	v_mov_b32_e32 v2, v237
	global_load_dword v237, v[34:35], off offset:96
	v_add_f32_e32 v2, v20, v2
	v_mul_f32_e32 v43, v69, v2
	v_and_b32_e32 v44, 0x7fffffff, v43
	v_cmp_nlt_f32_e64 s[2:3], |v43|, s60
	s_and_saveexec_b64 s[4:5], s[2:3]
	s_xor_b64 s[10:11], exec, s[4:5]
	s_cbranch_execnz .Lsl_203
.LBB0_203:
	s_andn2_saveexec_b64 s[2:3], s[10:11]
	v_mul_f32_e64 v2, |v43|, s1
	v_rndne_f32_e32 v2, v2
	v_cvt_i32_f32_e32 v45, v2
	v_fma_f32 v46, v2, s92, |v43|
	v_fmac_f32_e32 v46, 0xb3a22168, v2
	v_fmac_f32_e32 v46, 0xa7c234c4, v2
	s_or_b64 exec, exec, s[2:3]
	s_waitcnt vmcnt(19)
	v_mov_b32_e32 v2, v238
	global_load_dword v238, v[34:35], off offset:224
	v_add_f32_e32 v2, v4, v2
	v_mul_f32_e32 v4, v70, v2
	v_and_b32_e32 v20, 0x7fffffff, v4
	v_cmp_nlt_f32_e64 s[2:3], |v4|, s60
	s_and_saveexec_b64 s[4:5], s[2:3]
	s_xor_b64 s[10:11], exec, s[4:5]
	s_cbranch_execnz .Lsl_207
.LBB0_207:
	s_andn2_saveexec_b64 s[2:3], s[10:11]
	v_mul_f32_e64 v2, |v4|, s1
	v_rndne_f32_e32 v2, v2
	v_cvt_i32_f32_e32 v53, v2
	v_fma_f32 v54, v2, s92, |v4|
	v_fmac_f32_e32 v54, 0xb3a22168, v2
	v_fmac_f32_e32 v54, 0xa7c234c4, v2
	s_or_b64 exec, exec, s[2:3]
	s_waitcnt vmcnt(19)
	v_mov_b32_e32 v2, v239
	global_load_dword v239, v[34:35], off offset:100
	v_add_f32_e32 v2, v21, v2
	v_mul_f32_e32 v47, v71, v2
	v_and_b32_e32 v57, 0x7fffffff, v47
	v_cmp_nlt_f32_e64 s[2:3], |v47|, s60
	s_and_saveexec_b64 s[4:5], s[2:3]
	s_xor_b64 s[10:11], exec, s[4:5]
	s_cbranch_execnz .Lsl_211
.LBB0_211:
	s_andn2_saveexec_b64 s[2:3], s[10:11]
	v_mul_f32_e64 v2, |v47|, s1
	v_rndne_f32_e32 v2, v2
	v_cvt_i32_f32_e32 v58, v2
	v_fma_f32 v59, v2, s92, |v47|
	v_fmac_f32_e32 v59, 0xb3a22168, v2
	v_fmac_f32_e32 v59, 0xa7c234c4, v2
	s_or_b64 exec, exec, s[2:3]
	s_waitcnt vmcnt(19)
	v_mov_b32_e32 v2, v240
	global_load_dword v240, v[34:35], off offset:228
	v_add_f32_e32 v2, v5, v2
	v_mul_f32_e32 v5, v72, v2
	v_and_b32_e32 v21, 0x7fffffff, v5
	v_cmp_nlt_f32_e64 s[2:3], |v5|, s60
	s_and_saveexec_b64 s[4:5], s[2:3]
	s_xor_b64 s[10:11], exec, s[4:5]
	s_cbranch_execnz .Lsl_215
.LBB0_215:
	s_andn2_saveexec_b64 s[2:3], s[10:11]
	v_mul_f32_e64 v2, |v5|, s1
	v_rndne_f32_e32 v2, v2
	v_cvt_i32_f32_e32 v55, v2
	v_fma_f32 v56, v2, s92, |v5|
	v_fmac_f32_e32 v56, 0xb3a22168, v2
	v_fmac_f32_e32 v56, 0xa7c234c4, v2
	s_or_b64 exec, exec, s[2:3]
	s_waitcnt vmcnt(19)
	v_mov_b32_e32 v2, v241
	global_load_dword v241, v[34:35], off offset:104
	v_add_f32_e32 v2, v22, v2
	v_mul_f32_e32 v62, v73, v2
	v_and_b32_e32 v63, 0x7fffffff, v62
	v_cmp_nlt_f32_e64 s[2:3], |v62|, s60
	s_and_saveexec_b64 s[4:5], s[2:3]
	s_xor_b64 s[10:11], exec, s[4:5]
	s_cbranch_execnz .Lsl_219
; __device__ __forceinline__ int crow16(int r, int hi) { return (r & 3) + 8 * (r >> 2) + 4 * hi; }
; __device__ __forceinline__ void filter_item32(const Args& a, int L, bf16* KR, int t0, int np0, int npn, int lane) {
;     ...
;         for (int r = 0; r < 16; ++r) { const int j = crow16(r, hi); h0[r] = sinf(fq[j] * (g0[r] + bb[j])); h1[r] = sinf(fq[32 + j] * (g1[r] + bb[32 + j])); }
.LBB0_219:
	s_andn2_saveexec_b64 s[2:3], s[10:11]
	v_mul_f32_e64 v2, |v62|, s1
	v_rndne_f32_e32 v2, v2
	v_cvt_i32_f32_e32 v152, v2
	v_fma_f32 v153, v2, s92, |v62|
	v_fmac_f32_e32 v153, 0xb3a22168, v2
	v_fmac_f32_e32 v153, 0xa7c234c4, v2
	s_or_b64 exec, exec, s[2:3]
	s_waitcnt vmcnt(19)
	v_mov_b32_e32 v2, v244
	global_load_dword v244, v[34:35], off offset:232
	v_add_f32_e32 v2, v6, v2
	v_mul_f32_e32 v6, v74, v2
	v_and_b32_e32 v22, 0x7fffffff, v6
	v_cmp_nlt_f32_e64 s[2:3], |v6|, s60
	s_and_saveexec_b64 s[4:5], s[2:3]
	s_xor_b64 s[10:11], exec, s[4:5]
	s_cbranch_execnz .Lsl_223
.LBB0_223:
	s_andn2_saveexec_b64 s[2:3], s[10:11]
	v_mul_f32_e64 v2, |v6|, s1
	v_rndne_f32_e32 v2, v2
	v_cvt_i32_f32_e32 v60, v2
	v_fma_f32 v61, v2, s92, |v6|
	v_fmac_f32_e32 v61, 0xb3a22168, v2
	v_fmac_f32_e32 v61, 0xa7c234c4, v2
	s_or_b64 exec, exec, s[2:3]
	s_waitcnt vmcnt(19)
	v_mov_b32_e32 v2, v245
	global_load_dword v245, v[34:35], off offset:108
	v_add_f32_e32 v2, v23, v2
	v_mul_f32_e32 v156, v75, v2
	v_and_b32_e32 v157, 0x7fffffff, v156
	v_cmp_nlt_f32_e64 s[2:3], |v156|, s60
	s_and_saveexec_b64 s[4:5], s[2:3]
	s_xor_b64 s[10:11], exec, s[4:5]
	s_cbranch_execnz .Lsl_227
.LBB0_227:
	s_andn2_saveexec_b64 s[2:3], s[10:11]
	v_mul_f32_e64 v2, |v156|, s1
	v_rndne_f32_e32 v2, v2
	v_cvt_i32_f32_e32 v158, v2
	v_fma_f32 v159, v2, s92, |v156|
	v_fmac_f32_e32 v159, 0xb3a22168, v2
	v_fmac_f32_e32 v159, 0xa7c234c4, v2
	s_or_b64 exec, exec, s[2:3]
	s_waitcnt vmcnt(19)
	v_mov_b32_e32 v2, v246
	global_load_dword v246, v[34:35], off offset:236
	v_add_f32_e32 v2, v7, v2
	v_mul_f32_e32 v7, v76, v2
	v_and_b32_e32 v23, 0x7fffffff, v7
	v_cmp_nlt_f32_e64 s[2:3], |v7|, s60
	s_and_saveexec_b64 s[4:5], s[2:3]
	s_xor_b64 s[10:11], exec, s[4:5]
	s_cbranch_execnz .Lsl_231
.LBB0_231:
	s_andn2_saveexec_b64 s[2:3], s[10:11]
	v_mul_f32_e64 v2, |v7|, s1
	v_rndne_f32_e32 v2, v2
	v_cvt_i32_f32_e32 v154, v2
	v_fma_f32 v155, v2, s92, |v7|
	v_fmac_f32_e32 v155, 0xb3a22168, v2
	v_fmac_f32_e32 v155, 0xa7c234c4, v2
	s_or_b64 exec, exec, s[2:3]
	s_waitcnt vmcnt(19)
	v_mov_b32_e32 v2, v247
	v_add_f32_e32 v2, v24, v2
	v_mul_f32_e32 v164, v77, v2
	v_and_b32_e32 v165, 0x7fffffff, v164
	v_cmp_nlt_f32_e64 s[2:3], |v164|, s60
	s_and_saveexec_b64 s[4:5], s[2:3]
	s_xor_b64 s[10:11], exec, s[4:5]
	s_cbranch_execnz .Lsl_235
.LBB0_235:
	s_andn2_saveexec_b64 s[2:3], s[10:11]
	v_mul_f32_e64 v2, |v164|, s1
	v_rndne_f32_e32 v2, v2
	v_cvt_i32_f32_e32 v166, v2
	v_fma_f32 v167, v2, s92, |v164|
	v_fmac_f32_e32 v167, 0xb3a22168, v2
	v_fmac_f32_e32 v167, 0xa7c234c4, v2
	s_or_b64 exec, exec, s[2:3]
	s_waitcnt vmcnt(18)
	v_mov_b32_e32 v2, v248
	v_add_f32_e32 v2, v8, v2
	v_mul_f32_e32 v8, v78, v2
	v_and_b32_e32 v24, 0x7fffffff, v8
	v_cmp_nlt_f32_e64 s[2:3], |v8|, s60
	s_and_saveexec_b64 s[4:5], s[2:3]
	s_xor_b64 s[10:11], exec, s[4:5]
	s_cbranch_execnz .Lsl_239
.LBB0_239:
	s_andn2_saveexec_b64 s[2:3], s[10:11]
	v_mul_f32_e64 v2, |v8|, s1
	v_rndne_f32_e32 v2, v2
	v_cvt_i32_f32_e32 v161, v2
	v_fma_f32 v163, v2, s92, |v8|
	v_fmac_f32_e32 v163, 0xb3a22168, v2
	v_fmac_f32_e32 v163, 0xa7c234c4, v2
	s_or_b64 exec, exec, s[2:3]
	s_waitcnt vmcnt(17)
	v_mov_b32_e32 v2, v249
	v_add_f32_e32 v2, v25, v2
	v_mul_f32_e32 v170, v79, v2
	v_and_b32_e32 v171, 0x7fffffff, v170
	v_cmp_nlt_f32_e64 s[2:3], |v170|, s60
	s_and_saveexec_b64 s[4:5], s[2:3]
	s_xor_b64 s[10:11], exec, s[4:5]
	s_cbranch_execnz .Lsl_243
.LBB0_243:
	s_andn2_saveexec_b64 s[2:3], s[10:11]
	v_mul_f32_e64 v2, |v170|, s1
	v_rndne_f32_e32 v2, v2
	v_cvt_i32_f32_e32 v172, v2
	v_fma_f32 v173, v2, s92, |v170|
	v_fmac_f32_e32 v173, 0xb3a22168, v2
	v_fmac_f32_e32 v173, 0xa7c234c4, v2
	s_or_b64 exec, exec, s[2:3]
	s_waitcnt vmcnt(16)
	v_mov_b32_e32 v2, v250
	v_add_f32_e32 v2, v9, v2
	v_mul_f32_e32 v9, v112, v2
	v_and_b32_e32 v25, 0x7fffffff, v9
	v_cmp_nlt_f32_e64 s[2:3], |v9|, s60
	s_and_saveexec_b64 s[4:5], s[2:3]
	s_xor_b64 s[10:11], exec, s[4:5]
	s_cbranch_execnz .Lsl_247
.LBB0_247:
	s_andn2_saveexec_b64 s[2:3], s[10:11]
	v_mul_f32_e64 v2, |v9|, s1
	v_rndne_f32_e32 v2, v2
	v_cvt_i32_f32_e32 v168, v2
	v_fma_f32 v169, v2, s92, |v9|
	v_fmac_f32_e32 v169, 0xb3a22168, v2
	v_fmac_f32_e32 v169, 0xa7c234c4, v2
	s_or_b64 exec, exec, s[2:3]
	s_waitcnt vmcnt(15)
	v_mov_b32_e32 v2, v251
	v_add_f32_e32 v2, v26, v2
	v_mul_f32_e32 v176, v113, v2
	v_and_b32_e32 v177, 0x7fffffff, v176
	v_cmp_nlt_f32_e64 s[2:3], |v176|, s60
	s_and_saveexec_b64 s[4:5], s[2:3]
	s_xor_b64 s[10:11], exec, s[4:5]
	s_cbranch_execnz .Lsl_251
.LBB0_251:
	s_andn2_saveexec_b64 s[2:3], s[10:11]
	v_mul_f32_e64 v2, |v176|, s1
	v_rndne_f32_e32 v2, v2
	v_cvt_i32_f32_e32 v178, v2
	v_fma_f32 v179, v2, s92, |v176|
	v_fmac_f32_e32 v179, 0xb3a22168, v2
	v_fmac_f32_e32 v179, 0xa7c234c4, v2
	s_or_b64 exec, exec, s[2:3]
	s_waitcnt vmcnt(14)
	v_mov_b32_e32 v2, v252
	v_add_f32_e32 v2, v10, v2
	v_mul_f32_e32 v10, v114, v2
	v_and_b32_e32 v26, 0x7fffffff, v10
	v_cmp_nlt_f32_e64 s[2:3], |v10|, s60
	s_and_saveexec_b64 s[4:5], s[2:3]
	s_xor_b64 s[10:11], exec, s[4:5]
	s_cbranch_execnz .Lsl_255
.LBB0_255:
	s_andn2_saveexec_b64 s[2:3], s[10:11]
	v_mul_f32_e64 v2, |v10|, s1
	v_rndne_f32_e32 v2, v2
	v_cvt_i32_f32_e32 v174, v2
	v_fma_f32 v175, v2, s92, |v10|
	v_fmac_f32_e32 v175, 0xb3a22168, v2
	v_fmac_f32_e32 v175, 0xa7c234c4, v2
	s_or_b64 exec, exec, s[2:3]
	s_waitcnt vmcnt(13)
	v_mov_b32_e32 v2, v253
	v_add_f32_e32 v2, v27, v2
	v_mul_f32_e32 v182, v115, v2
	v_and_b32_e32 v183, 0x7fffffff, v182
	v_cmp_nlt_f32_e64 s[2:3], |v182|, s60
	s_and_saveexec_b64 s[4:5], s[2:3]
	s_xor_b64 s[10:11], exec, s[4:5]
	s_cbranch_execnz .Lsl_259
; __device__ __forceinline__ int crow16(int r, int hi) { return (r & 3) + 8 * (r >> 2) + 4 * hi; }
; __device__ __forceinline__ void filter_item32(const Args& a, int L, bf16* KR, int t0, int np0, int npn, int lane) {
;     ...
;         for (int r = 0; r < 16; ++r) { const int j = crow16(r, hi); h0[r] = sinf(fq[j] * (g0[r] + bb[j])); h1[r] = sinf(fq[32 + j] * (g1[r] + bb[32 + j])); }
.LBB0_259:
	s_andn2_saveexec_b64 s[2:3], s[10:11]
	v_mul_f32_e64 v2, |v182|, s1
	v_rndne_f32_e32 v2, v2
	v_cvt_i32_f32_e32 v184, v2
	v_fma_f32 v185, v2, s92, |v182|
	v_fmac_f32_e32 v185, 0xb3a22168, v2
	v_fmac_f32_e32 v185, 0xa7c234c4, v2
	s_or_b64 exec, exec, s[2:3]
	s_waitcnt vmcnt(12)
	v_mov_b32_e32 v2, v254
	v_add_f32_e32 v2, v11, v2
	v_mul_f32_e32 v11, v116, v2
	v_and_b32_e32 v27, 0x7fffffff, v11
	v_cmp_nlt_f32_e64 s[2:3], |v11|, s60
	s_and_saveexec_b64 s[4:5], s[2:3]
	s_xor_b64 s[10:11], exec, s[4:5]
	s_cbranch_execnz .Lsl_263
.LBB0_263:
	s_andn2_saveexec_b64 s[2:3], s[10:11]
	v_mul_f32_e64 v2, |v11|, s1
	v_rndne_f32_e32 v2, v2
	v_cvt_i32_f32_e32 v180, v2
	v_fma_f32 v181, v2, s92, |v11|
	v_fmac_f32_e32 v181, 0xb3a22168, v2
	v_fmac_f32_e32 v181, 0xa7c234c4, v2
	s_or_b64 exec, exec, s[2:3]
	s_waitcnt vmcnt(11)
	v_mov_b32_e32 v2, v255
	v_add_f32_e32 v2, v28, v2
	v_mul_f32_e32 v188, v117, v2
	v_and_b32_e32 v189, 0x7fffffff, v188
	v_cmp_nlt_f32_e64 s[2:3], |v188|, s60
	s_and_saveexec_b64 s[4:5], s[2:3]
	s_xor_b64 s[10:11], exec, s[4:5]
	s_cbranch_execnz .Lsl_267
.LBB0_267:
	s_andn2_saveexec_b64 s[2:3], s[10:11]
	v_mul_f32_e64 v2, |v188|, s1
	v_rndne_f32_e32 v2, v2
	v_cvt_i32_f32_e32 v190, v2
	v_fma_f32 v191, v2, s92, |v188|
	v_fmac_f32_e32 v191, 0xb3a22168, v2
	v_fmac_f32_e32 v191, 0xa7c234c4, v2
	s_or_b64 exec, exec, s[2:3]
	s_waitcnt vmcnt(10)
	v_mov_b32_e32 v2, v234
	v_add_f32_e32 v2, v12, v2
	v_mul_f32_e32 v12, v118, v2
	v_and_b32_e32 v28, 0x7fffffff, v12
	v_cmp_nlt_f32_e64 s[2:3], |v12|, s60
	s_and_saveexec_b64 s[4:5], s[2:3]
	s_xor_b64 s[10:11], exec, s[4:5]
	s_cbranch_execnz .Lsl_271
.LBB0_271:
	s_andn2_saveexec_b64 s[2:3], s[10:11]
	v_mul_f32_e64 v2, |v12|, s1
	v_rndne_f32_e32 v2, v2
	v_cvt_i32_f32_e32 v186, v2
	v_fma_f32 v187, v2, s92, |v12|
	v_fmac_f32_e32 v187, 0xb3a22168, v2
	v_fmac_f32_e32 v187, 0xa7c234c4, v2
	s_or_b64 exec, exec, s[2:3]
	s_waitcnt vmcnt(9)
	v_mov_b32_e32 v2, v235
	v_add_f32_e32 v2, v29, v2
	v_mul_f32_e32 v194, v119, v2
	v_and_b32_e32 v195, 0x7fffffff, v194
	v_cmp_nlt_f32_e64 s[2:3], |v194|, s60
	s_and_saveexec_b64 s[4:5], s[2:3]
	s_xor_b64 s[10:11], exec, s[4:5]
	s_cbranch_execnz .Lsl_275
.LBB0_275:
	s_andn2_saveexec_b64 s[2:3], s[10:11]
	v_mul_f32_e64 v2, |v194|, s1
	v_rndne_f32_e32 v2, v2
	v_cvt_i32_f32_e32 v196, v2
	v_fma_f32 v197, v2, s92, |v194|
	v_fmac_f32_e32 v197, 0xb3a22168, v2
	v_fmac_f32_e32 v197, 0xa7c234c4, v2
	s_or_b64 exec, exec, s[2:3]
	s_waitcnt vmcnt(8)
	v_mov_b32_e32 v2, v236
	v_add_f32_e32 v2, v13, v2
	v_mul_f32_e32 v13, v120, v2
	v_and_b32_e32 v29, 0x7fffffff, v13
	v_cmp_nlt_f32_e64 s[2:3], |v13|, s60
	s_and_saveexec_b64 s[4:5], s[2:3]
	s_xor_b64 s[10:11], exec, s[4:5]
	s_cbranch_execnz .Lsl_279
.LBB0_279:
	s_andn2_saveexec_b64 s[2:3], s[10:11]
	v_mul_f32_e64 v2, |v13|, s1
	v_rndne_f32_e32 v2, v2
	v_cvt_i32_f32_e32 v192, v2
	v_fma_f32 v193, v2, s92, |v13|
	v_fmac_f32_e32 v193, 0xb3a22168, v2
	v_fmac_f32_e32 v193, 0xa7c234c4, v2
	s_or_b64 exec, exec, s[2:3]
	s_waitcnt vmcnt(7)
	v_mov_b32_e32 v2, v237
	v_add_f32_e32 v2, v30, v2
	v_mul_f32_e32 v200, v121, v2
	v_and_b32_e32 v201, 0x7fffffff, v200
	v_cmp_nlt_f32_e64 s[2:3], |v200|, s60
	s_and_saveexec_b64 s[4:5], s[2:3]
	s_xor_b64 s[10:11], exec, s[4:5]
	s_cbranch_execnz .Lsl_283
.LBB0_283:
	s_andn2_saveexec_b64 s[2:3], s[10:11]
	v_mul_f32_e64 v2, |v200|, s1
	v_rndne_f32_e32 v2, v2
	v_cvt_i32_f32_e32 v202, v2
	v_fma_f32 v203, v2, s92, |v200|
	v_fmac_f32_e32 v203, 0xb3a22168, v2
	v_fmac_f32_e32 v203, 0xa7c234c4, v2
	s_or_b64 exec, exec, s[2:3]
	s_waitcnt vmcnt(6)
	v_mov_b32_e32 v2, v238
	v_add_f32_e32 v2, v14, v2
	v_mul_f32_e32 v14, v122, v2
	v_and_b32_e32 v30, 0x7fffffff, v14
	v_cmp_nlt_f32_e64 s[2:3], |v14|, s60
	s_and_saveexec_b64 s[4:5], s[2:3]
	s_xor_b64 s[10:11], exec, s[4:5]
	s_cbranch_execnz .Lsl_287
.LBB0_287:
	s_andn2_saveexec_b64 s[2:3], s[10:11]
	v_mul_f32_e64 v2, |v14|, s1
	v_rndne_f32_e32 v2, v2
	v_cvt_i32_f32_e32 v198, v2
	v_fma_f32 v199, v2, s92, |v14|
	v_fmac_f32_e32 v199, 0xb3a22168, v2
	v_fmac_f32_e32 v199, 0xa7c234c4, v2
	s_or_b64 exec, exec, s[2:3]
	s_waitcnt vmcnt(5)
	v_mov_b32_e32 v2, v239
	v_add_f32_e32 v2, v31, v2
	v_mul_f32_e32 v206, v123, v2
	v_and_b32_e32 v207, 0x7fffffff, v206
	v_cmp_nlt_f32_e64 s[2:3], |v206|, s60
	s_and_saveexec_b64 s[4:5], s[2:3]
	s_xor_b64 s[10:11], exec, s[4:5]
	s_cbranch_execnz .Lsl_291
.LBB0_291:
	s_andn2_saveexec_b64 s[2:3], s[10:11]
	v_mul_f32_e64 v2, |v206|, s1
	v_rndne_f32_e32 v2, v2
	v_cvt_i32_f32_e32 v208, v2
	v_fma_f32 v209, v2, s92, |v206|
	v_fmac_f32_e32 v209, 0xb3a22168, v2
	v_fmac_f32_e32 v209, 0xa7c234c4, v2
	s_or_b64 exec, exec, s[2:3]
	s_waitcnt vmcnt(4)
	v_mov_b32_e32 v2, v240
	v_add_f32_e32 v2, v15, v2
	v_mul_f32_e32 v15, v124, v2
	v_and_b32_e32 v31, 0x7fffffff, v15
	v_cmp_nlt_f32_e64 s[2:3], |v15|, s60
	s_and_saveexec_b64 s[4:5], s[2:3]
	s_xor_b64 s[10:11], exec, s[4:5]
	s_cbranch_execnz .Lsl_295
.LBB0_295:
	s_andn2_saveexec_b64 s[2:3], s[10:11]
	v_mul_f32_e64 v2, |v15|, s1
	v_rndne_f32_e32 v2, v2
	v_cvt_i32_f32_e32 v204, v2
	v_fma_f32 v205, v2, s92, |v15|
	v_fmac_f32_e32 v205, 0xb3a22168, v2
	v_fmac_f32_e32 v205, 0xa7c234c4, v2
	s_or_b64 exec, exec, s[2:3]
	s_waitcnt vmcnt(3)
	v_mov_b32_e32 v2, v241
	v_add_f32_e32 v2, v32, v2
	v_mul_f32_e32 v212, v125, v2
	v_and_b32_e32 v213, 0x7fffffff, v212
	v_cmp_nlt_f32_e64 s[2:3], |v212|, s60
	s_and_saveexec_b64 s[4:5], s[2:3]
	s_xor_b64 s[10:11], exec, s[4:5]
	s_cbranch_execnz .Lsl_299
.LBB0_299:
	s_andn2_saveexec_b64 s[2:3], s[10:11]
	v_mul_f32_e64 v2, |v212|, s1
	v_rndne_f32_e32 v2, v2
	v_cvt_i32_f32_e32 v214, v2
	v_fma_f32 v215, v2, s92, |v212|
	v_fmac_f32_e32 v215, 0xb3a22168, v2
	v_fmac_f32_e32 v215, 0xa7c234c4, v2
	s_or_b64 exec, exec, s[2:3]
	s_waitcnt vmcnt(2)
	v_mov_b32_e32 v2, v244
	v_add_f32_e32 v2, v16, v2
	v_mul_f32_e32 v16, v126, v2
	v_and_b32_e32 v32, 0x7fffffff, v16
	v_cmp_nlt_f32_e64 s[2:3], |v16|, s60
	s_and_saveexec_b64 s[4:5], s[2:3]
	s_xor_b64 s[10:11], exec, s[4:5]
	s_cbranch_execnz .Lsl_303
.LBB0_303:
	s_andn2_saveexec_b64 s[2:3], s[10:11]
	v_mul_f32_e64 v2, |v16|, s1
	v_rndne_f32_e32 v2, v2
	v_cvt_i32_f32_e32 v210, v2
	v_fma_f32 v211, v2, s92, |v16|
	v_fmac_f32_e32 v211, 0xb3a22168, v2
	v_fmac_f32_e32 v211, 0xa7c234c4, v2
	s_or_b64 exec, exec, s[2:3]
	s_waitcnt vmcnt(1)
	v_mov_b32_e32 v2, v245
	v_add_f32_e32 v2, v33, v2
	v_mul_f32_e32 v217, v127, v2
	v_and_b32_e32 v218, 0x7fffffff, v217
	v_cmp_nlt_f32_e64 s[2:3], |v217|, s60
	s_and_saveexec_b64 s[4:5], s[2:3]
	s_xor_b64 s[10:11], exec, s[4:5]
	s_cbranch_execnz .Lsl_307
.LBB0_307:
	s_andn2_saveexec_b64 s[2:3], s[10:11]
	v_mul_f32_e64 v2, |v217|, s1
	v_rndne_f32_e32 v2, v2
	v_cvt_i32_f32_e32 v219, v2
	v_fma_f32 v220, v2, s92, |v217|
	v_fmac_f32_e32 v220, 0xb3a22168, v2
	v_fmac_f32_e32 v220, 0xa7c234c4, v2
	s_or_b64 exec, exec, s[2:3]
	s_waitcnt vmcnt(0)
	v_mov_b32_e32 v2, v246
	v_add_f32_e32 v2, v17, v2
	v_mul_f32_e32 v17, v151, v2
	v_and_b32_e32 v33, 0x7fffffff, v17
	v_cmp_nlt_f32_e64 s[2:3], |v17|, s60
	s_and_saveexec_b64 s[4:5], s[2:3]
	s_xor_b64 s[10:11], exec, s[4:5]
	s_cbranch_execnz .Lsl_311

; #define LAS __attribute__((address_space(3)))
; __device__ __forceinline__ void hyena_unit(ldsp lds, const Args& a, const bf16* UT, const bf16* KRP, const bf16* KRS, bf16* YT, int unit, int tid, int wid, int lane) {
;     ...
;     { const int nz = (nseq * SP) >> 4; for (int i = tid; i < nz; i += 512) *(LAS v4u*)(lds + HY_SOFF + i * 16) = (v4u){0u, 0u, 0u, 0u};
;       if (tid < 4) *(LAS v4u*)(lds + 4 * L + tid * 16) = (v4u){0u, 0u, 0u, 0u}; }
;     { const int nc = (4 * L) >> 4; for (int i = tid; i < nc; i += 512) *(LAS v4u*)(lds + i * 16) = *(const v4u*)((const char*)KR + (size_t)i * 16); }
.LBB0_913:
	v_add_u32_e32 v2, 0x200, v2
	v_cmp_le_u32_e32 vcc, s6, v2
	ds_write_b128 v0, v[154:157]
	s_or_b64 s[4:5], vcc, s[4:5]
	v_add_u32_e32 v0, 0x2000, v0
	s_andn2_b64 exec, exec, s[4:5]
	s_cbranch_execnz .LBB0_913
	s_or_b64 exec, exec, s[4:5]
	s_and_saveexec_b64 s[4:5], s[0:1]
	v_add_u32_e32 v0, s80, v115
	ds_write_b128 v0, v[154:157]
	s_or_b64 exec, exec, s[4:5]
	s_add_i32 s4, s77, 0xfffffe00
	s_lshr_b32 s6, s4, 1
	s_and_b64 s[4:5], s[2:3], exec
	s_cselect_b32 s18, s77, s6
	s_lshr_b32 s8, s78, 2
	s_ashr_i32 s19, s18, 31
	v_cmp_gt_u32_e32 vcc, s8, v160
	s_and_saveexec_b64 s[4:5], vcc
	s_cbranch_execz .LBB0_919
	s_and_b64 s[6:7], s[2:3], exec
	s_cselect_b32 s7, s93, s96
	s_cselect_b32 s6, s86, s87
	s_cselect_b32 s9, 15, 12
	s_lshl_b64 s[10:11], s[18:19], s9
	v_lshl_add_u64 v[2:3], s[6:7], 0, v[102:103]
	v_lshl_add_u64 v[2:3], s[10:11], 1, v[2:3]
	s_mov_b64 s[6:7], 0
	v_mov_b32_e32 v0, v115
	v_mov_b32_e32 v4, v160
	s_cmpk_eq_u32 s8, 0x1000
	s_cbranch_scc0 .LBB0_918
	s_mov_b64 s[10:11], 0x2000
	global_load_dwordx4 v[190:193], v[2:3], off
	v_lshl_add_u64 v[2:3], v[2:3], 0, s[10:11]
	global_load_dwordx4 v[194:197], v[2:3], off
	v_lshl_add_u64 v[2:3], v[2:3], 0, s[10:11]
	global_load_dwordx4 v[198:201], v[2:3], off
	v_lshl_add_u64 v[2:3], v[2:3], 0, s[10:11]
	global_load_dwordx4 v[202:205], v[2:3], off
	v_lshl_add_u64 v[2:3], v[2:3], 0, s[10:11]
	global_load_dwordx4 v[206:209], v[2:3], off
	v_lshl_add_u64 v[2:3], v[2:3], 0, s[10:11]
	global_load_dwordx4 v[210:213], v[2:3], off
	v_lshl_add_u64 v[2:3], v[2:3], 0, s[10:11]
	global_load_dwordx4 v[214:217], v[2:3], off
	v_lshl_add_u64 v[2:3], v[2:3], 0, s[10:11]
	global_load_dwordx4 v[218:221], v[2:3], off
	v_lshl_add_u64 v[2:3], v[2:3], 0, s[10:11]
	s_waitcnt vmcnt(7)
	ds_write_b128 v0, v[190:193]
	v_add_u32_e32 v0, 0x2000, v0
	s_waitcnt vmcnt(6)
	ds_write_b128 v0, v[194:197]
	v_add_u32_e32 v0, 0x2000, v0
	s_waitcnt vmcnt(5)
	ds_write_b128 v0, v[198:201]
	v_add_u32_e32 v0, 0x2000, v0
	s_waitcnt vmcnt(4)
	ds_write_b128 v0, v[202:205]
	v_add_u32_e32 v0, 0x2000, v0
	s_waitcnt vmcnt(3)
	ds_write_b128 v0, v[206:209]
	v_add_u32_e32 v0, 0x2000, v0
	s_waitcnt vmcnt(2)
	ds_write_b128 v0, v[210:213]
	v_add_u32_e32 v0, 0x2000, v0
	s_waitcnt vmcnt(1)
	ds_write_b128 v0, v[214:217]
	v_add_u32_e32 v0, 0x2000, v0
	s_waitcnt vmcnt(0)
	ds_write_b128 v0, v[218:221]
	v_add_u32_e32 v0, 0x2000, v0
	v_add_u32_e32 v4, 0x1000, v4
	s_branch .LBB0_919
